# v37 + six provably-satisfied s_waitcnt vmcnt(4) removed from the dense attention loops
# speedup vs baseline: 1.0042x; 1.0042x over previous
; __device__ __forceinline__ void finishSM(f32x16& p0, f32x16& p1, float alpha, float& l_reg, bf16x8& pa0, bf16x8& pa1, bf16x8& pa2, bf16x8& pa3) {
; #pragma unroll
;   for (int r = 0; r < 16; ++r) p1[r] = __builtin_amdgcn_exp2f(p1[r]);
;   float ps = 0;
; #pragma unroll
;   for (int r = 0; r < 16; ++r) ps += p0[r];
; #pragma unroll
;   for (int r = 0; r < 16; ++r) ps += p1[r];
;   { auto rr = __builtin_amdgcn_permlane32_swap(__float_as_uint(ps), __float_as_uint(ps), false, false);
;     ps = __uint_as_float(rr[0]) + __uint_as_float(rr[1]); }
;   l_reg = l_reg * alpha + ps;
;   PK4(p0, 0, pa0); PK4(p0, 8, pa1); PK4(p1, 0, pa2); PK4(p1, 8, pa3);
; }
;   p0 = f32x16{}; p1 = f32x16{};
; #pragma unroll
;   for (int d0 = DLO; d0 < DHI; ++d0) { int cb = (d0 * 16 + hi * 8) * 2;
;     bf16x8 b0 = *reinterpret_cast<const bf16x8*>((const char*)Ks + KSWZ(r32, cb));
;     bf16x8 b1 = *reinterpret_cast<const bf16x8*>((const char*)Ks + KSWZ(32 + r32, cb));
;     p0 = __builtin_amdgcn_mfma_f32_32x32x16_bf16(b0, qr[d0], p0, 0, 0, 0);
;     p1 = __builtin_amdgcn_mfma_f32_32x32x16_bf16(b1, qr[d0], p1, 0, 0, 0); }
; }
; __device__ __forceinline__ int v_st(int k, int c) { const int kk = (k & ~0xC) | ((k & 4) << 1) | ((k & 8) >> 1); return ((kk >> 3) * 4 + (c >> 5)) * 512 + ((kk & 7) * 32 + (c & 31)) * 2; }
; __device__ __forceinline__ int v_rd_base(int lane) { return ((lane & 3) << 3) | (((lane >> 2) & 3) << 6) | (((lane >> 4) & 1) << 5) | (((lane >> 5) & 1) << 8); }
; template <int OFF> __device__ __forceinline__ s16x4 tr_read(int vb) {
;   s16x4 r; asm volatile("ds_read_b64_tr_b16 %0, %1 offset:%2" : "=&v"(r) : "v"(vb), "i"(OFF) : "memory"); return r;
; }
; template <int D0> __device__ __forceinline__ void pv_one(f32x16& od, int vb, bf16x8 pa0, bf16x8 pa1, bf16x8 pa2, bf16x8 pa3) {
;   const s16x4 l0 = tr_read<v_rd_off(D0, 0, 0)>(vb), h0 = tr_read<v_rd_off(D0, 0, 1)>(vb), l1 = tr_read<v_rd_off(D0, 1, 0)>(vb), h1 = tr_read<v_rd_off(D0, 1, 1)>(vb);
;   const s16x4 l2 = tr_read<v_rd_off(D0, 2, 0)>(vb), h2 = tr_read<v_rd_off(D0, 2, 1)>(vb), l3 = tr_read<v_rd_off(D0, 3, 0)>(vb), h3 = tr_read<v_rd_off(D0, 3, 1)>(vb);
;   asm volatile("s_waitcnt lgkmcnt(0)" ::: "memory"); SBAR();
;     ...
;   od = __builtin_amdgcn_mfma_f32_32x32x16_bf16(pa0, PK(l0, h0), od, 0, 0, 0);
;   od = __builtin_amdgcn_mfma_f32_32x32x16_bf16(pa1, PK(l1, h1), od, 0, 0, 0);
.LBB0_1002:
	ds_read_b128 v[66:69], v190 offset:49152
	ds_read_b128 v[70:73], v190 offset:57344
	ds_read_b128 v[186:189], v194 offset:49152
	ds_read_b128 v[208:211], v194 offset:57344
	ds_read_b128 v[232:235], v195 offset:49152
	ds_read_b128 v[236:239], v195 offset:57344
	ds_read_b128 v[240:243], v196 offset:49152
	ds_read_b128 v[244:247], v196 offset:57344
	v_add_f32_e32 v146, 0, v161
	v_add_f32_e32 v146, v167, v146
	v_add_f32_e32 v146, v147, v146
	s_waitcnt lgkmcnt(6)
	v_mfma_f32_32x32x16_bf16 v[82:97], v[66:69], v[102:105], 0
	v_add_f32_e32 v146, v166, v146
	v_add_f32_e32 v146, v148, v146
	v_add_f32_e32 v146, v160, v146
	v_add_f32_e32 v146, v149, v146
	v_add_f32_e32 v146, v159, v146
	v_add_f32_e32 v146, v156, v146
	v_mfma_f32_32x32x16_bf16 v[66:81], v[70:73], v[102:105], 0
	v_add_f32_e32 v146, v158, v146
	v_add_f32_e32 v146, v154, v146
	v_add_f32_e32 v146, v157, v146
	v_exp_f32_e32 v142, v142
	v_add_f32_e32 v146, v152, v146
	v_exp_f32_e32 v143, v143
	v_add_f32_e32 v146, v155, v146
	s_waitcnt lgkmcnt(4)
	v_mfma_f32_32x32x16_bf16 v[82:97], v[186:189], v[98:101], v[82:97]
	v_exp_f32_e32 v140, v140
	v_add_f32_e32 v146, v151, v146
	v_exp_f32_e32 v141, v141
	v_add_f32_e32 v146, v153, v146
	v_exp_f32_e32 v134, v134
	v_add_f32_e32 v146, v142, v146
	v_exp_f32_e32 v135, v135
	v_mfma_f32_32x32x16_bf16 v[66:81], v[208:211], v[98:101], v[66:81]
	v_add_f32_e32 v146, v143, v146
	v_exp_f32_e32 v132, v132
	v_add_f32_e32 v146, v140, v146
	v_exp_f32_e32 v133, v133
	v_add_f32_e32 v146, v141, v146
	v_exp_f32_e32 v130, v130
	s_waitcnt lgkmcnt(2)
	v_mfma_f32_32x32x16_bf16 v[82:97], v[232:235], v[106:109], v[82:97]
	v_add_f32_e32 v146, v134, v146
	v_exp_f32_e32 v131, v131
	v_add_f32_e32 v146, v135, v146
	v_exp_f32_e32 v144, v144
	v_add_f32_e32 v146, v132, v146
	v_exp_f32_e32 v145, v145
	v_add_f32_e32 v146, v133, v146
	v_mfma_f32_32x32x16_bf16 v[66:81], v[236:239], v[106:109], v[66:81]
	v_exp_f32_e32 v138, v138
	v_add_f32_e32 v146, v130, v146
	v_exp_f32_e32 v139, v139
	v_add_f32_e32 v146, v131, v146
	v_exp_f32_e32 v136, v136
	v_add_f32_e32 v146, v144, v146
	s_waitcnt lgkmcnt(0)
	v_mfma_f32_32x32x16_bf16 v[82:97], v[240:243], v[110:113], v[82:97]
	v_exp_f32_e32 v137, v137
	v_add_f32_e32 v146, v145, v146
	v_add_f32_e32 v146, v138, v146
	v_add_f32_e32 v146, v139, v146
	v_add_f32_e32 v146, v136, v146
	v_add_f32_e32 v207, v137, v146
	v_cvt_pk_bf16_f32 v146, v161, v167
	v_mfma_f32_32x32x16_bf16 v[66:81], v[244:247], v[110:113], v[66:81]
	v_mov_b32_e32 v208, v207
	v_cvt_pk_bf16_f32 v147, v147, v166
	v_cvt_pk_bf16_f32 v148, v148, v160
	s_nop 1
	v_permlane32_swap_b32_e32 v207, v208
	v_cvt_pk_bf16_f32 v149, v149, v159
	v_permlane32_swap_b32_e32 v146, v148
	v_cvt_pk_bf16_f32 v156, v156, v158
	v_cvt_pk_bf16_f32 v157, v154, v157
	v_cvt_pk_bf16_f32 v158, v152, v155
	v_cvt_pk_bf16_f32 v159, v151, v153
	v_cvt_pk_bf16_f32 v152, v142, v143
	v_cvt_pk_bf16_f32 v153, v140, v141
	v_cvt_pk_bf16_f32 v154, v134, v135
	v_cvt_pk_bf16_f32 v155, v132, v133
	v_cvt_pk_bf16_f32 v186, v130, v131
	v_cvt_pk_bf16_f32 v187, v144, v145
	v_cvt_pk_bf16_f32 v188, v138, v139
	v_cvt_pk_bf16_f32 v189, v136, v137
	v_permlane32_swap_b32_e32 v147, v149
	v_permlane32_swap_b32_e32 v156, v158
	v_permlane32_swap_b32_e32 v157, v159
	v_permlane32_swap_b32_e32 v152, v154
	v_permlane32_swap_b32_e32 v153, v155
	v_permlane32_swap_b32_e32 v186, v188
	v_permlane32_swap_b32_e32 v187, v189
	s_waitcnt vmcnt(0)
	ds_write_b128 v192, v[114:117]
	ds_write_b128 v193, v[118:121]
	ds_write_b128 v177, v[122:125] offset:32768
	ds_write_b128 v191, v[126:129] offset:32768
	v_lshl_add_u64 v[168:169], v[164:165], 0, v[0:1]
	s_mov_b32 s1, 0x18fb0000
	v_add_co_u32_e32 v130, vcc, s1, v168
	s_mov_b32 s1, 0x18ff8000
	s_nop 0
	v_addc_co_u32_e32 v131, vcc, 0, v169, vcc
	v_add_co_u32_e32 v134, vcc, s1, v168
	v_lshl_add_u64 v[166:167], v[162:163], 0, v[0:1]
	s_nop 0
	v_addc_co_u32_e32 v135, vcc, 0, v169, vcc
	s_mov_b32 s1, 0x1f648000
	v_add_co_u32_e32 v138, vcc, s1, v166
	s_mov_b32 s1, 0x1f654000
	s_nop 0
	v_addc_co_u32_e32 v139, vcc, 0, v167, vcc
	v_add_co_u32_e32 v142, vcc, s1, v166
	global_load_dwordx4 v[130:133], v[130:131], off
	s_nop 0
	global_load_dwordx4 v[134:137], v[134:135], off
	v_addc_co_u32_e32 v143, vcc, 0, v167, vcc
	global_load_dwordx4 v[138:141], v[138:139], off
	s_nop 0
	global_load_dwordx4 v[142:145], v[142:143], off
	ds_read_b64_tr_b16 v[210:211], v176 offset:0
	ds_read_b64_tr_b16 v[212:213], v176 offset:0x800
	ds_read_b64_tr_b16 v[214:215], v176 offset:0x1000
	ds_read_b64_tr_b16 v[216:217], v176 offset:0x1800
	ds_read_b64_tr_b16 v[218:219], v176 offset:0x2000
	ds_read_b64_tr_b16 v[220:221], v176 offset:0x2800
	ds_read_b64_tr_b16 v[222:223], v176 offset:0x3000
	ds_read_b64_tr_b16 v[224:225], v176 offset:0x3800
	s_waitcnt lgkmcnt(4)
	s_nop 0
	v_mfma_f32_32x32x16_bf16 v[2:17], v[146:149], v[210:213], v[2:17]
	ds_read_b64_tr_b16 v[210:211], v176 offset:0x200
	ds_read_b64_tr_b16 v[212:213], v176 offset:0xa00
	v_mfma_f32_32x32x16_bf16 v[2:17], v[156:159], v[214:217], v[2:17]
	ds_read_b64_tr_b16 v[214:215], v176 offset:0x1200
	ds_read_b64_tr_b16 v[216:217], v176 offset:0x1a00
	s_waitcnt lgkmcnt(4)
; #define SBAR() __builtin_amdgcn_sched_barrier(0)
; __device__ __forceinline__ void partialSM(f32x16& p0, f32x16& p1, float& m_reg, float& mn, float& alpha) {
;   constexpr float C = SCALE * 1.4426950408889634f;
;   float pmax = p0[0];
; #pragma unroll
;   for (int r = 1; r < 16; ++r) pmax = fmaxf(pmax, p0[r]);
; #pragma unroll
;   for (int r = 0; r < 16; ++r) pmax = fmaxf(pmax, p1[r]);
;   { auto rr = __builtin_amdgcn_permlane32_swap(__float_as_uint(pmax), __float_as_uint(pmax), false, false);
;     pmax = fmaxf(__uint_as_float(rr[0]), __uint_as_float(rr[1])); }
;   if (__builtin_expect(__all(pmax - m_reg <= THR / SCALE), 1)) { mn = m_reg; alpha = 1.f; }
;   else { mn = fmaxf(m_reg, pmax); alpha = __builtin_amdgcn_exp2f((m_reg - mn) * C); m_reg = mn; }
; template <int D0> __device__ __forceinline__ void pv_one(f32x16& od, int vb, bf16x8 pa0, bf16x8 pa1, bf16x8 pa2, bf16x8 pa3) {
;   const s16x4 l0 = tr_read<v_rd_off(D0, 0, 0)>(vb), h0 = tr_read<v_rd_off(D0, 0, 1)>(vb), l1 = tr_read<v_rd_off(D0, 1, 0)>(vb), h1 = tr_read<v_rd_off(D0, 1, 1)>(vb);
;   const s16x4 l2 = tr_read<v_rd_off(D0, 2, 0)>(vb), h2 = tr_read<v_rd_off(D0, 2, 1)>(vb), l3 = tr_read<v_rd_off(D0, 3, 0)>(vb), h3 = tr_read<v_rd_off(D0, 3, 1)>(vb);
;   asm volatile("s_waitcnt lgkmcnt(0)" ::: "memory"); SBAR();
;     ...
;   od = __builtin_amdgcn_mfma_f32_32x32x16_bf16(pa0, PK(l0, h0), od, 0, 0, 0);
;   od = __builtin_amdgcn_mfma_f32_32x32x16_bf16(pa1, PK(l1, h1), od, 0, 0, 0);
;   od = __builtin_amdgcn_mfma_f32_32x32x16_bf16(pa2, PK(l2, h2), od, 0, 0, 0);
;   od = __builtin_amdgcn_mfma_f32_32x32x16_bf16(pa3, PK(l3, h3), od, 0, 0, 0);
;     ...
; }
; __device__ __forceinline__ void pv_d0(f32x16* o, int vb, bf16x8 pa0, bf16x8 pa1, bf16x8 pa2, bf16x8 pa3) {
;   pv_one<0>(o[0], vb, pa0, pa1, pa2, pa3); pv_one<1>(o[1], vb, pa0, pa1, pa2, pa3); pv_one<2>(o[2], vb, pa0, pa1, pa2, pa3); pv_one<3>(o[3], vb, pa0, pa1, pa2, pa3);
; }
; template <int DLO, int DHI>
; __device__ __forceinline__ void attn_dense_body(const int g_wave, const bf16* __restrict__ Qb, const bf16* __restrict__ Kh, const bf16* __restrict__ Vh,
;                                                 bf16* __restrict__ Ob, int ldo, char* lds) {
;   const int wid = launder_s(g_wave), lane = opaque_lane(), tid = (wid << 6) | lane, r32 = lane & 31, hi = lane >> 5;
;   bf16* V_lds = (bf16*)lds; bf16* K_lds = (bf16*)(lds + 2 * SHM_V);
	v_mfma_f32_32x32x16_bf16 v[2:17], v[152:155], v[218:221], v[2:17]
	ds_read_b64_tr_b16 v[218:219], v176 offset:0x2200
	ds_read_b64_tr_b16 v[220:221], v176 offset:0x2a00
	v_mfma_f32_32x32x16_bf16 v[2:17], v[186:189], v[222:225], v[2:17]
	ds_read_b64_tr_b16 v[222:223], v176 offset:0x3200
	ds_read_b64_tr_b16 v[224:225], v176 offset:0x3a00
	s_waitcnt lgkmcnt(4)
	v_mfma_f32_32x32x16_bf16 v[50:65], v[146:149], v[210:213], v[50:65]
	ds_read_b64_tr_b16 v[210:211], v176 offset:0x400
	ds_read_b64_tr_b16 v[212:213], v176 offset:0xc00
	v_mfma_f32_32x32x16_bf16 v[50:65], v[156:159], v[214:217], v[50:65]
	ds_read_b64_tr_b16 v[214:215], v176 offset:0x1400
	ds_read_b64_tr_b16 v[216:217], v176 offset:0x1c00
	s_waitcnt lgkmcnt(4)
	v_mfma_f32_32x32x16_bf16 v[50:65], v[152:155], v[218:221], v[50:65]
	ds_read_b64_tr_b16 v[218:219], v176 offset:0x2400
	ds_read_b64_tr_b16 v[220:221], v176 offset:0x2c00
	v_mfma_f32_32x32x16_bf16 v[50:65], v[186:189], v[222:225], v[50:65]
	ds_read_b64_tr_b16 v[222:223], v176 offset:0x3400
	ds_read_b64_tr_b16 v[224:225], v176 offset:0x3c00
	s_waitcnt lgkmcnt(4)
	v_mfma_f32_32x32x16_bf16 v[34:49], v[146:149], v[210:213], v[34:49]
	ds_read_b64_tr_b16 v[210:211], v176 offset:0x600
	ds_read_b64_tr_b16 v[212:213], v176 offset:0xe00
	v_mfma_f32_32x32x16_bf16 v[34:49], v[156:159], v[214:217], v[34:49]
	ds_read_b64_tr_b16 v[214:215], v176 offset:0x1600
	ds_read_b64_tr_b16 v[216:217], v176 offset:0x1e00
	s_waitcnt lgkmcnt(4)
	v_mfma_f32_32x32x16_bf16 v[34:49], v[152:155], v[218:221], v[34:49]
	ds_read_b64_tr_b16 v[218:219], v176 offset:0x2600
	ds_read_b64_tr_b16 v[220:221], v176 offset:0x2e00
	v_mfma_f32_32x32x16_bf16 v[34:49], v[186:189], v[222:225], v[34:49]
	ds_read_b64_tr_b16 v[222:223], v176 offset:0x3600
	ds_read_b64_tr_b16 v[224:225], v176 offset:0x3e00
	s_waitcnt lgkmcnt(4)
	v_mfma_f32_32x32x16_bf16 v[18:33], v[146:149], v[210:213], v[18:33]
	v_max_f32_e32 v146, v83, v83
	v_max_f32_e32 v147, v82, v82
	v_max_f32_e32 v146, v147, v146
	v_max3_f32 v146, v146, v84, v85
	v_max3_f32 v146, v146, v86, v87
	v_max3_f32 v146, v146, v88, v89
	v_max3_f32 v146, v146, v90, v91
	v_max3_f32 v146, v146, v92, v93
	v_max3_f32 v146, v146, v94, v95
	v_mfma_f32_32x32x16_bf16 v[18:33], v[156:159], v[214:217], v[18:33]
	v_max3_f32 v146, v146, v96, v97
	v_max3_f32 v146, v146, v66, v67
	v_max3_f32 v146, v146, v68, v69
	v_max3_f32 v146, v146, v70, v71
	v_max3_f32 v146, v146, v72, v73
	v_max3_f32 v146, v146, v74, v75
	v_max3_f32 v146, v146, v76, v77
	v_max3_f32 v146, v146, v78, v79
	s_waitcnt lgkmcnt(0)
	v_mfma_f32_32x32x16_bf16 v[18:33], v[152:155], v[218:221], v[18:33]
	v_max3_f32 v146, v146, v80, v81
	v_mov_b32_e32 v147, v146
	s_nop 1
	v_permlane32_swap_b32_e32 v146, v147
	v_max_f32_e32 v147, v147, v147
	v_max_f32_e32 v146, v146, v146
	v_max_f32_e32 v146, v146, v147
	v_sub_f32_e32 v147, v146, v150
	v_cmp_ge_f32_e32 vcc, s63, v147
	v_max_f32_e32 v147, v150, v150
	v_max_f32_e32 v146, v147, v146
	v_mfma_f32_32x32x16_bf16 v[18:33], v[186:189], v[222:225], v[18:33]
	v_sub_f32_e32 v147, v150, v146
	v_mul_f32_e32 v147, 0x3e0293ee, v147
	v_exp_f32_e32 v147, v147
	s_cmp_eq_u64 vcc, exec
	s_cselect_b64 s[8:9], -1, 0
	v_cndmask_b32_e64 v209, v147, 1.0, s[8:9]
	v_cmp_gt_f32_e32 vcc, 1.0, v209
	s_cbranch_vccz .LBB0_1006
	s_and_saveexec_b64 s[2:3], s[6:7]
	ds_write_b32 v173, v209 offset:128
	s_or_b64 exec, exec, s[2:3]
	s_waitcnt lgkmcnt(0)
	v_add_u32_e32 v147, s15, v172
	ds_read_b128 v[152:155], v147 offset:224
	ds_read_b128 v[156:159], v147 offset:192
	ds_read_b128 v[186:189], v147 offset:160
	ds_read_b128 v[210:213], v147 offset:128
	s_waitcnt lgkmcnt(3)
	v_pk_mul_f32 v[14:15], v[14:15], v[152:153]
	s_waitcnt lgkmcnt(2)
	v_pk_mul_f32 v[10:11], v[10:11], v[156:157]
	s_waitcnt lgkmcnt(1)
	v_pk_mul_f32 v[6:7], v[6:7], v[186:187]
	v_pk_mul_f32 v[16:17], v[16:17], v[154:155]
	v_pk_mul_f32 v[12:13], v[12:13], v[158:159]
	v_pk_mul_f32 v[8:9], v[8:9], v[188:189]
	s_waitcnt lgkmcnt(0)
	v_pk_mul_f32 v[4:5], v[4:5], v[212:213]
	v_pk_mul_f32 v[2:3], v[2:3], v[210:211]
	v_pk_mul_f32 v[62:63], v[62:63], v[152:153]
	v_pk_mul_f32 v[58:59], v[58:59], v[156:157]
	v_pk_mul_f32 v[54:55], v[54:55], v[186:187]
	v_pk_mul_f32 v[64:65], v[64:65], v[154:155]
	v_pk_mul_f32 v[60:61], v[60:61], v[158:159]
	v_pk_mul_f32 v[56:57], v[56:57], v[188:189]
	v_pk_mul_f32 v[52:53], v[52:53], v[212:213]
	v_pk_mul_f32 v[50:51], v[50:51], v[210:211]
	v_pk_mul_f32 v[46:47], v[46:47], v[152:153]
	v_pk_mul_f32 v[42:43], v[42:43], v[156:157]
	v_pk_mul_f32 v[38:39], v[38:39], v[186:187]
	v_pk_mul_f32 v[48:49], v[48:49], v[154:155]
	v_pk_mul_f32 v[44:45], v[44:45], v[158:159]
	v_pk_mul_f32 v[40:41], v[40:41], v[188:189]
	v_pk_mul_f32 v[36:37], v[36:37], v[212:213]
	v_pk_mul_f32 v[34:35], v[34:35], v[210:211]
	v_pk_mul_f32 v[30:31], v[30:31], v[152:153]
	v_pk_mul_f32 v[26:27], v[26:27], v[156:157]
	v_pk_mul_f32 v[22:23], v[22:23], v[186:187]
	v_pk_mul_f32 v[32:33], v[32:33], v[154:155]
	v_pk_mul_f32 v[28:29], v[28:29], v[158:159]
	v_pk_mul_f32 v[24:25], v[24:25], v[188:189]
	v_pk_mul_f32 v[20:21], v[20:21], v[212:213]
	v_pk_mul_f32 v[18:19], v[18:19], v[210:211]

; #define SBAR() __builtin_amdgcn_sched_barrier(0)
; __device__ __forceinline__ void partialSM(f32x16& p0, f32x16& p1, float& m_reg, float& mn, float& alpha) {
;   constexpr float C = SCALE * 1.4426950408889634f;
;   float pmax = p0[0];
; #pragma unroll
;   for (int r = 1; r < 16; ++r) pmax = fmaxf(pmax, p0[r]);
; #pragma unroll
;   for (int r = 0; r < 16; ++r) pmax = fmaxf(pmax, p1[r]);
;   { auto rr = __builtin_amdgcn_permlane32_swap(__float_as_uint(pmax), __float_as_uint(pmax), false, false);
;     pmax = fmaxf(__uint_as_float(rr[0]), __uint_as_float(rr[1])); }
;   if (__builtin_expect(__all(pmax - m_reg <= THR / SCALE), 1)) { mn = m_reg; alpha = 1.f; }
;   else { mn = fmaxf(m_reg, pmax); alpha = __builtin_amdgcn_exp2f((m_reg - mn) * C); m_reg = mn; }
; template <int D0> __device__ __forceinline__ void pv_one(f32x16& od, int vb, bf16x8 pa0, bf16x8 pa1, bf16x8 pa2, bf16x8 pa3) {
;   const s16x4 l0 = tr_read<v_rd_off(D0, 0, 0)>(vb), h0 = tr_read<v_rd_off(D0, 0, 1)>(vb), l1 = tr_read<v_rd_off(D0, 1, 0)>(vb), h1 = tr_read<v_rd_off(D0, 1, 1)>(vb);
;   const s16x4 l2 = tr_read<v_rd_off(D0, 2, 0)>(vb), h2 = tr_read<v_rd_off(D0, 2, 1)>(vb), l3 = tr_read<v_rd_off(D0, 3, 0)>(vb), h3 = tr_read<v_rd_off(D0, 3, 1)>(vb);
;   asm volatile("s_waitcnt lgkmcnt(0)" ::: "memory"); SBAR();
;     ...
;   od = __builtin_amdgcn_mfma_f32_32x32x16_bf16(pa0, PK(l0, h0), od, 0, 0, 0);
;   od = __builtin_amdgcn_mfma_f32_32x32x16_bf16(pa1, PK(l1, h1), od, 0, 0, 0);
;   od = __builtin_amdgcn_mfma_f32_32x32x16_bf16(pa2, PK(l2, h2), od, 0, 0, 0);
;   od = __builtin_amdgcn_mfma_f32_32x32x16_bf16(pa3, PK(l3, h3), od, 0, 0, 0);
;     ...
; }
; __device__ __forceinline__ void pv_d0(f32x16* o, int vb, bf16x8 pa0, bf16x8 pa1, bf16x8 pa2, bf16x8 pa3) {
;   pv_one<0>(o[0], vb, pa0, pa1, pa2, pa3); pv_one<1>(o[1], vb, pa0, pa1, pa2, pa3); pv_one<2>(o[2], vb, pa0, pa1, pa2, pa3); pv_one<3>(o[3], vb, pa0, pa1, pa2, pa3);
; }
; template <int DLO, int DHI>
; __device__ __forceinline__ void attn_dense_body(const int g_wave, const bf16* __restrict__ Qb, const bf16* __restrict__ Kh, const bf16* __restrict__ Vh,
;                                                 bf16* __restrict__ Ob, int ldo, char* lds) {
;   const int wid = launder_s(g_wave), lane = opaque_lane(), tid = (wid << 6) | lane, r32 = lane & 31, hi = lane >> 5;
;   bf16* V_lds = (bf16*)lds; bf16* K_lds = (bf16*)(lds + 2 * SHM_V);
.LBB0_1008:
	ds_read_b64_tr_b16 v[166:167], v175 offset:0
	ds_read_b64_tr_b16 v[168:169], v175 offset:0x800
	ds_read_b64_tr_b16 v[186:187], v175 offset:0x1000
	ds_read_b64_tr_b16 v[188:189], v175 offset:0x1800
	ds_read_b64_tr_b16 v[214:215], v175 offset:0x2000
	ds_read_b64_tr_b16 v[216:217], v175 offset:0x2800
	ds_read_b64_tr_b16 v[218:219], v175 offset:0x3000
	ds_read_b64_tr_b16 v[220:221], v175 offset:0x3800
	s_waitcnt lgkmcnt(4)
	s_nop 0
	v_mfma_f32_32x32x16_bf16 v[2:17], v[146:149], v[166:169], v[2:17]
	ds_read_b64_tr_b16 v[166:167], v175 offset:0x200
	ds_read_b64_tr_b16 v[168:169], v175 offset:0xa00
	v_mfma_f32_32x32x16_bf16 v[2:17], v[150:153], v[186:189], v[2:17]
	ds_read_b64_tr_b16 v[186:187], v175 offset:0x1200
	ds_read_b64_tr_b16 v[188:189], v175 offset:0x1a00
	s_waitcnt lgkmcnt(4)
	v_mfma_f32_32x32x16_bf16 v[2:17], v[154:157], v[214:217], v[2:17]
	ds_read_b64_tr_b16 v[214:215], v175 offset:0x2200
	ds_read_b64_tr_b16 v[216:217], v175 offset:0x2a00
	v_mfma_f32_32x32x16_bf16 v[2:17], v[158:161], v[218:221], v[2:17]
	ds_read_b64_tr_b16 v[218:219], v175 offset:0x3200
	ds_read_b64_tr_b16 v[220:221], v175 offset:0x3a00
	s_waitcnt lgkmcnt(4)
	v_mfma_f32_32x32x16_bf16 v[50:65], v[146:149], v[166:169], v[50:65]
	ds_read_b64_tr_b16 v[166:167], v175 offset:0x400
	ds_read_b64_tr_b16 v[168:169], v175 offset:0xc00
	v_mfma_f32_32x32x16_bf16 v[50:65], v[150:153], v[186:189], v[50:65]
	ds_read_b64_tr_b16 v[186:187], v175 offset:0x1400
	ds_read_b64_tr_b16 v[188:189], v175 offset:0x1c00
	s_waitcnt lgkmcnt(4)
	v_mfma_f32_32x32x16_bf16 v[50:65], v[154:157], v[214:217], v[50:65]
	ds_read_b64_tr_b16 v[214:215], v175 offset:0x2400
	ds_read_b64_tr_b16 v[216:217], v175 offset:0x2c00
	v_mfma_f32_32x32x16_bf16 v[50:65], v[158:161], v[218:221], v[50:65]
	ds_read_b64_tr_b16 v[218:219], v175 offset:0x3400
	ds_read_b64_tr_b16 v[220:221], v175 offset:0x3c00
	s_waitcnt lgkmcnt(4)
	v_mfma_f32_32x32x16_bf16 v[34:49], v[146:149], v[166:169], v[34:49]
	ds_read_b64_tr_b16 v[166:167], v175 offset:0x600
	ds_read_b64_tr_b16 v[168:169], v175 offset:0xe00
	v_mfma_f32_32x32x16_bf16 v[34:49], v[150:153], v[186:189], v[34:49]
	ds_read_b64_tr_b16 v[186:187], v175 offset:0x1600
	ds_read_b64_tr_b16 v[188:189], v175 offset:0x1e00
	s_waitcnt lgkmcnt(4)
	v_mfma_f32_32x32x16_bf16 v[34:49], v[154:157], v[214:217], v[34:49]
	ds_read_b64_tr_b16 v[214:215], v175 offset:0x2600
	ds_read_b64_tr_b16 v[216:217], v175 offset:0x2e00
	v_mfma_f32_32x32x16_bf16 v[34:49], v[158:161], v[218:221], v[34:49]
	ds_read_b64_tr_b16 v[218:219], v175 offset:0x3600
	ds_read_b64_tr_b16 v[220:221], v175 offset:0x3e00
	s_waitcnt lgkmcnt(4)
	v_mfma_f32_32x32x16_bf16 v[18:33], v[146:149], v[166:169], v[18:33]
	v_max_f32_e32 v146, v83, v83
	v_max_f32_e32 v147, v82, v82
	v_max_f32_e32 v146, v147, v146
	v_max3_f32 v146, v146, v84, v85
	v_max3_f32 v146, v146, v86, v87
	v_max3_f32 v146, v146, v88, v89
	v_max3_f32 v146, v146, v90, v91
	v_max3_f32 v146, v146, v92, v93
	v_max3_f32 v146, v146, v94, v95
	v_mfma_f32_32x32x16_bf16 v[18:33], v[150:153], v[186:189], v[18:33]
	v_max3_f32 v146, v146, v96, v97
	v_max3_f32 v146, v146, v66, v67
	v_max3_f32 v146, v146, v68, v69
	v_max3_f32 v146, v146, v70, v71
	v_max3_f32 v146, v146, v72, v73
	v_max3_f32 v146, v146, v74, v75
	v_max3_f32 v146, v146, v76, v77
	v_max3_f32 v146, v146, v78, v79
	s_waitcnt lgkmcnt(0)
	v_mfma_f32_32x32x16_bf16 v[18:33], v[154:157], v[214:217], v[18:33]
	v_max3_f32 v146, v146, v80, v81
	v_mov_b32_e32 v147, v146
	s_nop 1
	v_permlane32_swap_b32_e32 v146, v147
	v_max_f32_e32 v147, v147, v147
	v_max_f32_e32 v146, v146, v146
	v_max_f32_e32 v146, v146, v147
	v_sub_f32_e32 v147, v146, v210
	v_cmp_ge_f32_e32 vcc, s63, v147
	v_max_f32_e32 v147, v210, v210
	v_max_f32_e32 v147, v147, v146
	v_mfma_f32_32x32x16_bf16 v[18:33], v[158:161], v[218:221], v[18:33]
	v_sub_f32_e32 v146, v210, v147
	v_mul_f32_e32 v146, 0x3e0293ee, v146
	v_exp_f32_e32 v146, v146
	s_cmp_eq_u64 vcc, exec
	s_cselect_b64 s[8:9], -1, 0
	v_cndmask_b32_e64 v146, v146, 1.0, s[8:9]
	v_cmp_gt_f32_e32 vcc, 1.0, v146
	s_cbranch_vccz .LBB0_1012
	s_and_saveexec_b64 s[4:5], s[6:7]
	ds_write_b32 v173, v146 offset:128
	s_or_b64 exec, exec, s[4:5]
	s_waitcnt lgkmcnt(0)
	v_add_u32_e32 v142, s15, v172
	ds_read_b128 v[130:133], v142 offset:224
	ds_read_b128 v[134:137], v142 offset:192
	ds_read_b128 v[138:141], v142 offset:160
	ds_read_b128 v[142:145], v142 offset:128
	s_waitcnt lgkmcnt(3)
	v_pk_mul_f32 v[14:15], v[14:15], v[130:131]
	s_waitcnt lgkmcnt(2)
	v_pk_mul_f32 v[10:11], v[10:11], v[134:135]
	s_waitcnt lgkmcnt(1)
	v_pk_mul_f32 v[6:7], v[6:7], v[138:139]
	v_pk_mul_f32 v[16:17], v[16:17], v[132:133]
	v_pk_mul_f32 v[12:13], v[12:13], v[136:137]
	v_pk_mul_f32 v[8:9], v[8:9], v[140:141]
	s_waitcnt lgkmcnt(0)
	v_pk_mul_f32 v[4:5], v[4:5], v[144:145]
	v_pk_mul_f32 v[2:3], v[2:3], v[142:143]
	v_pk_mul_f32 v[62:63], v[62:63], v[130:131]
	v_pk_mul_f32 v[58:59], v[58:59], v[134:135]
	v_pk_mul_f32 v[54:55], v[54:55], v[138:139]
	v_pk_mul_f32 v[64:65], v[64:65], v[132:133]
	v_pk_mul_f32 v[60:61], v[60:61], v[136:137]
	v_pk_mul_f32 v[56:57], v[56:57], v[140:141]
	v_pk_mul_f32 v[52:53], v[52:53], v[144:145]
	v_pk_mul_f32 v[50:51], v[50:51], v[142:143]
	v_pk_mul_f32 v[46:47], v[46:47], v[130:131]
	v_pk_mul_f32 v[42:43], v[42:43], v[134:135]
	v_pk_mul_f32 v[38:39], v[38:39], v[138:139]
	v_pk_mul_f32 v[48:49], v[48:49], v[132:133]
	v_pk_mul_f32 v[44:45], v[44:45], v[136:137]
	v_pk_mul_f32 v[40:41], v[40:41], v[140:141]
	v_pk_mul_f32 v[36:37], v[36:37], v[144:145]
	v_pk_mul_f32 v[34:35], v[34:35], v[142:143]
	v_pk_mul_f32 v[30:31], v[30:31], v[130:131]
	v_pk_mul_f32 v[26:27], v[26:27], v[134:135]
	v_pk_mul_f32 v[22:23], v[22:23], v[138:139]
	v_pk_mul_f32 v[32:33], v[32:33], v[132:133]
	v_pk_mul_f32 v[28:29], v[28:29], v[136:137]
	v_pk_mul_f32 v[24:25], v[24:25], v[140:141]
	v_pk_mul_f32 v[20:21], v[20:21], v[144:145]
	v_pk_mul_f32 v[18:19], v[18:19], v[142:143]

; __device__ __forceinline__ void finishSM(f32x16& p0, f32x16& p1, float alpha, float& l_reg, bf16x8& pa0, bf16x8& pa1, bf16x8& pa2, bf16x8& pa3) {
; #pragma unroll
;   for (int r = 0; r < 16; ++r) p1[r] = __builtin_amdgcn_exp2f(p1[r]);
;   float ps = 0;
; #pragma unroll
;   for (int r = 0; r < 16; ++r) ps += p0[r];
; #pragma unroll
;   for (int r = 0; r < 16; ++r) ps += p1[r];
;   { auto rr = __builtin_amdgcn_permlane32_swap(__float_as_uint(ps), __float_as_uint(ps), false, false);
;     ps = __uint_as_float(rr[0]) + __uint_as_float(rr[1]); }
;   l_reg = l_reg * alpha + ps;
;   PK4(p0, 0, pa0); PK4(p0, 8, pa1); PK4(p1, 0, pa2); PK4(p1, 8, pa3);
; }
;   p0 = f32x16{}; p1 = f32x16{};
; #pragma unroll
;   for (int d0 = DLO; d0 < DHI; ++d0) { int cb = (d0 * 16 + hi * 8) * 2;
;     bf16x8 b0 = *reinterpret_cast<const bf16x8*>((const char*)Ks + KSWZ(r32, cb));
;     bf16x8 b1 = *reinterpret_cast<const bf16x8*>((const char*)Ks + KSWZ(32 + r32, cb));
;     p0 = __builtin_amdgcn_mfma_f32_32x32x16_bf16(b0, qr[d0], p0, 0, 0, 0);
;     p1 = __builtin_amdgcn_mfma_f32_32x32x16_bf16(b1, qr[d0], p1, 0, 0, 0); }
; }
; __device__ __forceinline__ int v_st(int k, int c) { const int kk = (k & ~0xC) | ((k & 4) << 1) | ((k & 8) >> 1); return ((kk >> 3) * 4 + (c >> 5)) * 512 + ((kk & 7) * 32 + (c & 31)) * 2; }
; __device__ __forceinline__ int v_rd_base(int lane) { return ((lane & 3) << 3) | (((lane >> 2) & 3) << 6) | (((lane >> 4) & 1) << 5) | (((lane >> 5) & 1) << 8); }
; template <int OFF> __device__ __forceinline__ s16x4 tr_read(int vb) {
;   s16x4 r; asm volatile("ds_read_b64_tr_b16 %0, %1 offset:%2" : "=&v"(r) : "v"(vb), "i"(OFF) : "memory"); return r;
; }
; template <int D0> __device__ __forceinline__ void pv_one(f32x16& od, int vb, bf16x8 pa0, bf16x8 pa1, bf16x8 pa2, bf16x8 pa3) {
;   const s16x4 l0 = tr_read<v_rd_off(D0, 0, 0)>(vb), h0 = tr_read<v_rd_off(D0, 0, 1)>(vb), l1 = tr_read<v_rd_off(D0, 1, 0)>(vb), h1 = tr_read<v_rd_off(D0, 1, 1)>(vb);
;   const s16x4 l2 = tr_read<v_rd_off(D0, 2, 0)>(vb), h2 = tr_read<v_rd_off(D0, 2, 1)>(vb), l3 = tr_read<v_rd_off(D0, 3, 0)>(vb), h3 = tr_read<v_rd_off(D0, 3, 1)>(vb);
;   asm volatile("s_waitcnt lgkmcnt(0)" ::: "memory"); SBAR();
;     ...
;   od = __builtin_amdgcn_mfma_f32_32x32x16_bf16(pa0, PK(l0, h0), od, 0, 0, 0);
;   od = __builtin_amdgcn_mfma_f32_32x32x16_bf16(pa1, PK(l1, h1), od, 0, 0, 0);
.LBB0_1022:
	ds_read_b128 v[66:69], v177 offset:49152
	ds_read_b128 v[70:73], v177 offset:57344
	ds_read_b128 v[186:189], v194 offset:49152
	ds_read_b128 v[208:211], v194 offset:57344
	ds_read_b128 v[232:235], v195 offset:49152
	ds_read_b128 v[236:239], v195 offset:57344
	ds_read_b128 v[240:243], v196 offset:49152
	ds_read_b128 v[244:247], v196 offset:57344
	v_add_f32_e32 v146, 0, v161
	v_add_f32_e32 v146, v167, v146
	v_add_f32_e32 v146, v147, v146
	s_waitcnt lgkmcnt(6)
	v_mfma_f32_32x32x16_bf16 v[82:97], v[66:69], v[102:105], 0
	v_add_f32_e32 v146, v166, v146
	v_add_f32_e32 v146, v148, v146
	v_add_f32_e32 v146, v160, v146
	v_add_f32_e32 v146, v149, v146
	v_add_f32_e32 v146, v159, v146
	v_add_f32_e32 v146, v156, v146
	v_mfma_f32_32x32x16_bf16 v[66:81], v[70:73], v[102:105], 0
	v_add_f32_e32 v146, v158, v146
	v_add_f32_e32 v146, v154, v146
	v_add_f32_e32 v146, v157, v146
	v_exp_f32_e32 v142, v142
	v_add_f32_e32 v146, v152, v146
	v_exp_f32_e32 v143, v143
	v_add_f32_e32 v146, v155, v146
	s_waitcnt lgkmcnt(4)
	v_mfma_f32_32x32x16_bf16 v[82:97], v[186:189], v[98:101], v[82:97]
	v_exp_f32_e32 v140, v140
	v_add_f32_e32 v146, v151, v146
	v_exp_f32_e32 v141, v141
	v_add_f32_e32 v146, v153, v146
	v_exp_f32_e32 v134, v134
	v_add_f32_e32 v146, v142, v146
	v_exp_f32_e32 v135, v135
	v_mfma_f32_32x32x16_bf16 v[66:81], v[208:211], v[98:101], v[66:81]
	v_add_f32_e32 v146, v143, v146
	v_exp_f32_e32 v132, v132
	v_add_f32_e32 v146, v140, v146
	v_exp_f32_e32 v133, v133
	v_add_f32_e32 v146, v141, v146
	v_exp_f32_e32 v130, v130
	s_waitcnt lgkmcnt(2)
	v_mfma_f32_32x32x16_bf16 v[82:97], v[232:235], v[106:109], v[82:97]
	v_add_f32_e32 v146, v134, v146
	v_exp_f32_e32 v131, v131
	v_add_f32_e32 v146, v135, v146
	v_exp_f32_e32 v144, v144
	v_add_f32_e32 v146, v132, v146
	v_exp_f32_e32 v145, v145
	v_add_f32_e32 v146, v133, v146
	v_mfma_f32_32x32x16_bf16 v[66:81], v[236:239], v[106:109], v[66:81]
	v_exp_f32_e32 v138, v138
	v_add_f32_e32 v146, v130, v146
	v_exp_f32_e32 v139, v139
	v_add_f32_e32 v146, v131, v146
	v_exp_f32_e32 v136, v136
	v_add_f32_e32 v146, v144, v146
	s_waitcnt lgkmcnt(0)
	v_mfma_f32_32x32x16_bf16 v[82:97], v[240:243], v[110:113], v[82:97]
	v_exp_f32_e32 v137, v137
	v_add_f32_e32 v146, v145, v146
	v_add_f32_e32 v146, v138, v146
	v_add_f32_e32 v146, v139, v146
	v_add_f32_e32 v146, v136, v146
	v_add_f32_e32 v207, v137, v146
	v_cvt_pk_bf16_f32 v146, v161, v167
	v_mfma_f32_32x32x16_bf16 v[66:81], v[244:247], v[110:113], v[66:81]
	v_mov_b32_e32 v208, v207
	v_cvt_pk_bf16_f32 v147, v147, v166
	v_cvt_pk_bf16_f32 v148, v148, v160
	s_nop 1
	v_permlane32_swap_b32_e32 v207, v208
	v_cvt_pk_bf16_f32 v149, v149, v159
	v_permlane32_swap_b32_e32 v146, v148
	v_cvt_pk_bf16_f32 v156, v156, v158
	v_cvt_pk_bf16_f32 v157, v154, v157
	v_cvt_pk_bf16_f32 v158, v152, v155
	v_cvt_pk_bf16_f32 v159, v151, v153
	v_cvt_pk_bf16_f32 v152, v142, v143
	v_cvt_pk_bf16_f32 v153, v140, v141
	v_cvt_pk_bf16_f32 v154, v134, v135
	v_cvt_pk_bf16_f32 v155, v132, v133
	v_cvt_pk_bf16_f32 v186, v130, v131
	v_cvt_pk_bf16_f32 v187, v144, v145
	v_cvt_pk_bf16_f32 v188, v138, v139
	v_cvt_pk_bf16_f32 v189, v136, v137
	v_permlane32_swap_b32_e32 v147, v149
	v_permlane32_swap_b32_e32 v156, v158
	v_permlane32_swap_b32_e32 v157, v159
	v_permlane32_swap_b32_e32 v152, v154
	v_permlane32_swap_b32_e32 v153, v155
	v_permlane32_swap_b32_e32 v186, v188
	v_permlane32_swap_b32_e32 v187, v189
	s_waitcnt vmcnt(0)
	ds_write_b128 v192, v[114:117]
	ds_write_b128 v193, v[118:121]
	ds_write_b128 v190, v[122:125] offset:32768
	ds_write_b128 v191, v[126:129] offset:32768
	v_lshl_add_u64 v[168:169], v[164:165], 0, v[0:1]
	s_mov_b32 s1, 0x18fb0000
	v_add_co_u32_e32 v130, vcc, s1, v168
	s_mov_b32 s1, 0x18ff8000
	s_nop 0
	v_addc_co_u32_e32 v131, vcc, 0, v169, vcc
	v_add_co_u32_e32 v134, vcc, s1, v168
	v_lshl_add_u64 v[166:167], v[162:163], 0, v[0:1]
	s_nop 0
	v_addc_co_u32_e32 v135, vcc, 0, v169, vcc
	s_mov_b32 s1, 0x1f648000
	v_add_co_u32_e32 v138, vcc, s1, v166
	s_mov_b32 s1, 0x1f654000
	s_nop 0
	v_addc_co_u32_e32 v139, vcc, 0, v167, vcc
	v_add_co_u32_e32 v142, vcc, s1, v166
	global_load_dwordx4 v[130:133], v[130:131], off
	s_nop 0
	global_load_dwordx4 v[134:137], v[134:135], off
	v_addc_co_u32_e32 v143, vcc, 0, v167, vcc
	global_load_dwordx4 v[138:141], v[138:139], off
	s_nop 0
	global_load_dwordx4 v[142:145], v[142:143], off
	ds_read_b64_tr_b16 v[210:211], v176 offset:0
	ds_read_b64_tr_b16 v[212:213], v176 offset:0x800
	ds_read_b64_tr_b16 v[214:215], v176 offset:0x1000
	ds_read_b64_tr_b16 v[216:217], v176 offset:0x1800
	ds_read_b64_tr_b16 v[218:219], v176 offset:0x2000
	ds_read_b64_tr_b16 v[220:221], v176 offset:0x2800
	ds_read_b64_tr_b16 v[222:223], v176 offset:0x3000
	ds_read_b64_tr_b16 v[224:225], v176 offset:0x3800
	s_waitcnt lgkmcnt(4)
	s_nop 0
	v_mfma_f32_32x32x16_bf16 v[2:17], v[146:149], v[210:213], v[2:17]
	ds_read_b64_tr_b16 v[210:211], v176 offset:0x200
	ds_read_b64_tr_b16 v[212:213], v176 offset:0xa00
	v_mfma_f32_32x32x16_bf16 v[2:17], v[156:159], v[214:217], v[2:17]
	ds_read_b64_tr_b16 v[214:215], v176 offset:0x1200
	ds_read_b64_tr_b16 v[216:217], v176 offset:0x1a00
	s_waitcnt lgkmcnt(4)
; #define SBAR() __builtin_amdgcn_sched_barrier(0)
; __device__ __forceinline__ void partialSM(f32x16& p0, f32x16& p1, float& m_reg, float& mn, float& alpha) {
;   constexpr float C = SCALE * 1.4426950408889634f;
;   float pmax = p0[0];
; #pragma unroll
;   for (int r = 1; r < 16; ++r) pmax = fmaxf(pmax, p0[r]);
; #pragma unroll
;   for (int r = 0; r < 16; ++r) pmax = fmaxf(pmax, p1[r]);
;   { auto rr = __builtin_amdgcn_permlane32_swap(__float_as_uint(pmax), __float_as_uint(pmax), false, false);
;     pmax = fmaxf(__uint_as_float(rr[0]), __uint_as_float(rr[1])); }
;   if (__builtin_expect(__all(pmax - m_reg <= THR / SCALE), 1)) { mn = m_reg; alpha = 1.f; }
;   else { mn = fmaxf(m_reg, pmax); alpha = __builtin_amdgcn_exp2f((m_reg - mn) * C); m_reg = mn; }
; template <int D0> __device__ __forceinline__ void pv_one(f32x16& od, int vb, bf16x8 pa0, bf16x8 pa1, bf16x8 pa2, bf16x8 pa3) {
;   const s16x4 l0 = tr_read<v_rd_off(D0, 0, 0)>(vb), h0 = tr_read<v_rd_off(D0, 0, 1)>(vb), l1 = tr_read<v_rd_off(D0, 1, 0)>(vb), h1 = tr_read<v_rd_off(D0, 1, 1)>(vb);
;   const s16x4 l2 = tr_read<v_rd_off(D0, 2, 0)>(vb), h2 = tr_read<v_rd_off(D0, 2, 1)>(vb), l3 = tr_read<v_rd_off(D0, 3, 0)>(vb), h3 = tr_read<v_rd_off(D0, 3, 1)>(vb);
;   asm volatile("s_waitcnt lgkmcnt(0)" ::: "memory"); SBAR();
;     ...
;   od = __builtin_amdgcn_mfma_f32_32x32x16_bf16(pa0, PK(l0, h0), od, 0, 0, 0);
;   od = __builtin_amdgcn_mfma_f32_32x32x16_bf16(pa1, PK(l1, h1), od, 0, 0, 0);
;   od = __builtin_amdgcn_mfma_f32_32x32x16_bf16(pa2, PK(l2, h2), od, 0, 0, 0);
;   od = __builtin_amdgcn_mfma_f32_32x32x16_bf16(pa3, PK(l3, h3), od, 0, 0, 0);
;     ...
; }
; __device__ __forceinline__ void pv_d0(f32x16* o, int vb, bf16x8 pa0, bf16x8 pa1, bf16x8 pa2, bf16x8 pa3) {
;   pv_one<0>(o[0], vb, pa0, pa1, pa2, pa3); pv_one<1>(o[1], vb, pa0, pa1, pa2, pa3); pv_one<2>(o[2], vb, pa0, pa1, pa2, pa3); pv_one<3>(o[3], vb, pa0, pa1, pa2, pa3);
; }
; template <int DLO, int DHI>
; __device__ __forceinline__ void attn_dense_body(const int g_wave, const bf16* __restrict__ Qb, const bf16* __restrict__ Kh, const bf16* __restrict__ Vh,
;                                                 bf16* __restrict__ Ob, int ldo, char* lds) {
;   const int wid = launder_s(g_wave), lane = opaque_lane(), tid = (wid << 6) | lane, r32 = lane & 31, hi = lane >> 5;
;   bf16* V_lds = (bf16*)lds; bf16* K_lds = (bf16*)(lds + 2 * SHM_V);
	v_mfma_f32_32x32x16_bf16 v[2:17], v[152:155], v[218:221], v[2:17]
	ds_read_b64_tr_b16 v[218:219], v176 offset:0x2200
	ds_read_b64_tr_b16 v[220:221], v176 offset:0x2a00
	v_mfma_f32_32x32x16_bf16 v[2:17], v[186:189], v[222:225], v[2:17]
	ds_read_b64_tr_b16 v[222:223], v176 offset:0x3200
	ds_read_b64_tr_b16 v[224:225], v176 offset:0x3a00
	s_waitcnt lgkmcnt(4)
	v_mfma_f32_32x32x16_bf16 v[50:65], v[146:149], v[210:213], v[50:65]
	ds_read_b64_tr_b16 v[210:211], v176 offset:0x400
	ds_read_b64_tr_b16 v[212:213], v176 offset:0xc00
	v_mfma_f32_32x32x16_bf16 v[50:65], v[156:159], v[214:217], v[50:65]
	ds_read_b64_tr_b16 v[214:215], v176 offset:0x1400
	ds_read_b64_tr_b16 v[216:217], v176 offset:0x1c00
	s_waitcnt lgkmcnt(4)
	v_mfma_f32_32x32x16_bf16 v[50:65], v[152:155], v[218:221], v[50:65]
	ds_read_b64_tr_b16 v[218:219], v176 offset:0x2400
	ds_read_b64_tr_b16 v[220:221], v176 offset:0x2c00
	v_mfma_f32_32x32x16_bf16 v[50:65], v[186:189], v[222:225], v[50:65]
	ds_read_b64_tr_b16 v[222:223], v176 offset:0x3400
	ds_read_b64_tr_b16 v[224:225], v176 offset:0x3c00
	s_waitcnt lgkmcnt(4)
	v_mfma_f32_32x32x16_bf16 v[34:49], v[146:149], v[210:213], v[34:49]
	ds_read_b64_tr_b16 v[210:211], v176 offset:0x600
	ds_read_b64_tr_b16 v[212:213], v176 offset:0xe00
	v_mfma_f32_32x32x16_bf16 v[34:49], v[156:159], v[214:217], v[34:49]
	ds_read_b64_tr_b16 v[214:215], v176 offset:0x1600
	ds_read_b64_tr_b16 v[216:217], v176 offset:0x1e00
	s_waitcnt lgkmcnt(4)
	v_mfma_f32_32x32x16_bf16 v[34:49], v[152:155], v[218:221], v[34:49]
	ds_read_b64_tr_b16 v[218:219], v176 offset:0x2600
	ds_read_b64_tr_b16 v[220:221], v176 offset:0x2e00
	v_mfma_f32_32x32x16_bf16 v[34:49], v[186:189], v[222:225], v[34:49]
	ds_read_b64_tr_b16 v[222:223], v176 offset:0x3600
	ds_read_b64_tr_b16 v[224:225], v176 offset:0x3e00
	s_waitcnt lgkmcnt(4)
	v_mfma_f32_32x32x16_bf16 v[18:33], v[146:149], v[210:213], v[18:33]
	v_max_f32_e32 v146, v83, v83
	v_max_f32_e32 v147, v82, v82
	v_max_f32_e32 v146, v147, v146
	v_max3_f32 v146, v146, v84, v85
	v_max3_f32 v146, v146, v86, v87
	v_max3_f32 v146, v146, v88, v89
	v_max3_f32 v146, v146, v90, v91
	v_max3_f32 v146, v146, v92, v93
	v_max3_f32 v146, v146, v94, v95
	v_mfma_f32_32x32x16_bf16 v[18:33], v[156:159], v[214:217], v[18:33]
	v_max3_f32 v146, v146, v96, v97
	v_max3_f32 v146, v146, v66, v67
	v_max3_f32 v146, v146, v68, v69
	v_max3_f32 v146, v146, v70, v71
	v_max3_f32 v146, v146, v72, v73
	v_max3_f32 v146, v146, v74, v75
	v_max3_f32 v146, v146, v76, v77
	v_max3_f32 v146, v146, v78, v79
	s_waitcnt lgkmcnt(0)
	v_mfma_f32_32x32x16_bf16 v[18:33], v[152:155], v[218:221], v[18:33]
	v_max3_f32 v146, v146, v80, v81
	v_mov_b32_e32 v147, v146
	s_nop 1
	v_permlane32_swap_b32_e32 v146, v147
	v_max_f32_e32 v147, v147, v147
	v_max_f32_e32 v146, v146, v146
	v_max_f32_e32 v146, v146, v147
	v_sub_f32_e32 v147, v146, v150
	v_cmp_ge_f32_e32 vcc, s63, v147
	v_max_f32_e32 v147, v150, v150
	v_max_f32_e32 v146, v147, v146
	v_mfma_f32_32x32x16_bf16 v[18:33], v[186:189], v[222:225], v[18:33]
	v_sub_f32_e32 v147, v150, v146
	v_mul_f32_e32 v147, 0x3e0293ee, v147
	v_exp_f32_e32 v147, v147
	s_cmp_eq_u64 vcc, exec
	s_cselect_b64 s[8:9], -1, 0
	v_cndmask_b32_e64 v209, v147, 1.0, s[8:9]
	v_cmp_gt_f32_e32 vcc, 1.0, v209
	s_cbranch_vccz .LBB0_1026
	s_and_saveexec_b64 s[2:3], s[6:7]
	ds_write_b32 v173, v209 offset:128
	s_or_b64 exec, exec, s[2:3]
	s_waitcnt lgkmcnt(0)
	v_add_u32_e32 v147, s15, v172
	ds_read_b128 v[152:155], v147 offset:224
	ds_read_b128 v[156:159], v147 offset:192
	ds_read_b128 v[186:189], v147 offset:160
	ds_read_b128 v[210:213], v147 offset:128
	s_waitcnt lgkmcnt(3)
	v_pk_mul_f32 v[14:15], v[14:15], v[152:153]
	s_waitcnt lgkmcnt(2)
	v_pk_mul_f32 v[10:11], v[10:11], v[156:157]
	s_waitcnt lgkmcnt(1)
	v_pk_mul_f32 v[6:7], v[6:7], v[186:187]
	v_pk_mul_f32 v[16:17], v[16:17], v[154:155]
	v_pk_mul_f32 v[12:13], v[12:13], v[158:159]
	v_pk_mul_f32 v[8:9], v[8:9], v[188:189]
	s_waitcnt lgkmcnt(0)
	v_pk_mul_f32 v[4:5], v[4:5], v[212:213]
	v_pk_mul_f32 v[2:3], v[2:3], v[210:211]
	v_pk_mul_f32 v[62:63], v[62:63], v[152:153]
	v_pk_mul_f32 v[58:59], v[58:59], v[156:157]
	v_pk_mul_f32 v[54:55], v[54:55], v[186:187]
	v_pk_mul_f32 v[64:65], v[64:65], v[154:155]
	v_pk_mul_f32 v[60:61], v[60:61], v[158:159]
	v_pk_mul_f32 v[56:57], v[56:57], v[188:189]
	v_pk_mul_f32 v[52:53], v[52:53], v[212:213]
	v_pk_mul_f32 v[50:51], v[50:51], v[210:211]
	v_pk_mul_f32 v[46:47], v[46:47], v[152:153]
	v_pk_mul_f32 v[42:43], v[42:43], v[156:157]
	v_pk_mul_f32 v[38:39], v[38:39], v[186:187]
	v_pk_mul_f32 v[48:49], v[48:49], v[154:155]
	v_pk_mul_f32 v[44:45], v[44:45], v[158:159]
	v_pk_mul_f32 v[40:41], v[40:41], v[188:189]
	v_pk_mul_f32 v[36:37], v[36:37], v[212:213]
	v_pk_mul_f32 v[34:35], v[34:35], v[210:211]
	v_pk_mul_f32 v[30:31], v[30:31], v[152:153]
	v_pk_mul_f32 v[26:27], v[26:27], v[156:157]
	v_pk_mul_f32 v[22:23], v[22:23], v[186:187]
	v_pk_mul_f32 v[32:33], v[32:33], v[154:155]
	v_pk_mul_f32 v[28:29], v[28:29], v[158:159]
	v_pk_mul_f32 v[24:25], v[24:25], v[188:189]
	v_pk_mul_f32 v[20:21], v[20:21], v[212:213]
	v_pk_mul_f32 v[18:19], v[18:19], v[210:211]

; __device__ __forceinline__ void finishSM(f32x16& p0, f32x16& p1, float alpha, float& l_reg, bf16x8& pa0, bf16x8& pa1, bf16x8& pa2, bf16x8& pa3) {
; #pragma unroll
;   for (int r = 0; r < 16; ++r) p1[r] = __builtin_amdgcn_exp2f(p1[r]);
;   float ps = 0;
; #pragma unroll
;   for (int r = 0; r < 16; ++r) ps += p0[r];
; #pragma unroll
;   for (int r = 0; r < 16; ++r) ps += p1[r];
;   { auto rr = __builtin_amdgcn_permlane32_swap(__float_as_uint(ps), __float_as_uint(ps), false, false);
;     ps = __uint_as_float(rr[0]) + __uint_as_float(rr[1]); }
;   l_reg = l_reg * alpha + ps;
;   PK4(p0, 0, pa0); PK4(p0, 8, pa1); PK4(p1, 0, pa2); PK4(p1, 8, pa3);
; }
;   p0 = f32x16{}; p1 = f32x16{};
; #pragma unroll
;   for (int d0 = DLO; d0 < DHI; ++d0) { int cb = (d0 * 16 + hi * 8) * 2;
;     bf16x8 b0 = *reinterpret_cast<const bf16x8*>((const char*)Ks + KSWZ(r32, cb));
;     bf16x8 b1 = *reinterpret_cast<const bf16x8*>((const char*)Ks + KSWZ(32 + r32, cb));
;     p0 = __builtin_amdgcn_mfma_f32_32x32x16_bf16(b0, qr[d0], p0, 0, 0, 0);
;     p1 = __builtin_amdgcn_mfma_f32_32x32x16_bf16(b1, qr[d0], p1, 0, 0, 0); }
; }
; __device__ __forceinline__ int v_st(int k, int c) { const int kk = (k & ~0xC) | ((k & 4) << 1) | ((k & 8) >> 1); return ((kk >> 3) * 4 + (c >> 5)) * 512 + ((kk & 7) * 32 + (c & 31)) * 2; }
; __device__ __forceinline__ int v_rd_base(int lane) { return ((lane & 3) << 3) | (((lane >> 2) & 3) << 6) | (((lane >> 4) & 1) << 5) | (((lane >> 5) & 1) << 8); }
; template <int OFF> __device__ __forceinline__ s16x4 tr_read(int vb) {
;   s16x4 r; asm volatile("ds_read_b64_tr_b16 %0, %1 offset:%2" : "=&v"(r) : "v"(vb), "i"(OFF) : "memory"); return r;
; }
; template <int D0> __device__ __forceinline__ void pv_one(f32x16& od, int vb, bf16x8 pa0, bf16x8 pa1, bf16x8 pa2, bf16x8 pa3) {
;   const s16x4 l0 = tr_read<v_rd_off(D0, 0, 0)>(vb), h0 = tr_read<v_rd_off(D0, 0, 1)>(vb), l1 = tr_read<v_rd_off(D0, 1, 0)>(vb), h1 = tr_read<v_rd_off(D0, 1, 1)>(vb);
;   const s16x4 l2 = tr_read<v_rd_off(D0, 2, 0)>(vb), h2 = tr_read<v_rd_off(D0, 2, 1)>(vb), l3 = tr_read<v_rd_off(D0, 3, 0)>(vb), h3 = tr_read<v_rd_off(D0, 3, 1)>(vb);
;   asm volatile("s_waitcnt lgkmcnt(0)" ::: "memory"); SBAR();
;     ...
;   od = __builtin_amdgcn_mfma_f32_32x32x16_bf16(pa0, PK(l0, h0), od, 0, 0, 0);
;   od = __builtin_amdgcn_mfma_f32_32x32x16_bf16(pa1, PK(l1, h1), od, 0, 0, 0);
.LBB0_1043:
	ds_read_b128 v[66:69], v218 offset:49152
	ds_read_b128 v[70:73], v218 offset:57344
	ds_read_b128 v[186:189], v225 offset:49152
	ds_read_b128 v[230:233], v225 offset:57344
	ds_read_b128 v[234:237], v224 offset:49152
	ds_read_b128 v[238:241], v224 offset:57344
	ds_read_b128 v[242:245], v222 offset:49152
	ds_read_b128 v[246:249], v222 offset:57344
	v_add_f32_e32 v162, 0, v177
	v_add_f32_e32 v162, v195, v162
	s_waitcnt lgkmcnt(6)
	v_mfma_f32_32x32x16_bf16 v[82:97], v[66:69], v[118:121], 0
	v_add_f32_e32 v162, v163, v162
	v_add_f32_e32 v162, v194, v162
	v_add_f32_e32 v162, v164, v162
	v_add_f32_e32 v162, v176, v162
	v_add_f32_e32 v162, v165, v162
	v_add_f32_e32 v162, v175, v162
	v_add_f32_e32 v162, v166, v162
	v_mfma_f32_32x32x16_bf16 v[66:81], v[70:73], v[118:121], 0
	v_add_f32_e32 v162, v174, v162
	v_add_f32_e32 v162, v167, v162
	v_add_f32_e32 v162, v173, v162
	v_exp_f32_e32 v158, v158
	v_add_f32_e32 v162, v168, v162
	v_exp_f32_e32 v159, v159
	v_add_f32_e32 v162, v172, v162
	s_waitcnt lgkmcnt(4)
	v_mfma_f32_32x32x16_bf16 v[82:97], v[186:189], v[110:113], v[82:97]
	v_exp_f32_e32 v156, v156
	v_add_f32_e32 v162, v169, v162
	v_exp_f32_e32 v157, v157
	v_add_f32_e32 v162, v171, v162
	v_exp_f32_e32 v150, v150
	v_add_f32_e32 v162, v158, v162
	v_exp_f32_e32 v151, v151
	v_mfma_f32_32x32x16_bf16 v[66:81], v[230:233], v[110:113], v[66:81]
	ds_read_b128 v[186:189], v220 offset:49152
	ds_read_b128 v[230:233], v220 offset:57344
	v_add_f32_e32 v162, v159, v162
	v_exp_f32_e32 v148, v148
	v_add_f32_e32 v162, v156, v162
	v_exp_f32_e32 v149, v149
	v_add_f32_e32 v162, v157, v162
	v_exp_f32_e32 v146, v146
	s_waitcnt lgkmcnt(4)
	v_mfma_f32_32x32x16_bf16 v[82:97], v[234:237], v[126:129], v[82:97]
	v_add_f32_e32 v162, v150, v162
	v_exp_f32_e32 v147, v147
	v_add_f32_e32 v162, v151, v162
	v_exp_f32_e32 v160, v160
	v_add_f32_e32 v162, v148, v162
	v_exp_f32_e32 v161, v161
	v_add_f32_e32 v162, v149, v162
	v_mfma_f32_32x32x16_bf16 v[66:81], v[238:241], v[126:129], v[66:81]
	ds_read_b128 v[234:237], v219 offset:49152
	ds_read_b128 v[238:241], v219 offset:57344
	v_exp_f32_e32 v154, v154
	v_add_f32_e32 v162, v146, v162
	v_exp_f32_e32 v155, v155
	v_add_f32_e32 v162, v147, v162
	v_exp_f32_e32 v152, v152
	v_add_f32_e32 v162, v160, v162
	s_waitcnt lgkmcnt(4)
	v_mfma_f32_32x32x16_bf16 v[82:97], v[242:245], v[122:125], v[82:97]
	v_exp_f32_e32 v153, v153
	v_add_f32_e32 v162, v161, v162
	v_add_f32_e32 v162, v154, v162
	v_add_f32_e32 v162, v155, v162
	v_add_f32_e32 v162, v152, v162
	v_add_f32_e32 v227, v153, v162
	v_mfma_f32_32x32x16_bf16 v[66:81], v[246:249], v[122:125], v[66:81]
	ds_read_b128 v[242:245], v221 offset:49152
	ds_read_b128 v[246:249], v221 offset:57344
	s_waitcnt lgkmcnt(4)
	v_mfma_f32_32x32x16_bf16 v[82:97], v[186:189], v[114:117], v[82:97]
	v_mfma_f32_32x32x16_bf16 v[66:81], v[230:233], v[114:117], v[66:81]
	ds_read_b128 v[186:189], v223 offset:49152
	ds_read_b128 v[230:233], v223 offset:57344
	s_waitcnt lgkmcnt(4)
	v_mfma_f32_32x32x16_bf16 v[82:97], v[234:237], v[106:109], v[82:97]
	v_mfma_f32_32x32x16_bf16 v[66:81], v[238:241], v[106:109], v[66:81]
	s_waitcnt lgkmcnt(2)
	v_mfma_f32_32x32x16_bf16 v[82:97], v[242:245], v[102:105], v[82:97]
	v_mfma_f32_32x32x16_bf16 v[66:81], v[246:249], v[102:105], v[66:81]
	v_cvt_pk_bf16_f32 v162, v177, v195
	v_cvt_pk_bf16_f32 v163, v163, v194
	v_cvt_pk_bf16_f32 v164, v164, v176
	v_cvt_pk_bf16_f32 v165, v165, v175
	v_cvt_pk_bf16_f32 v166, v166, v174
	v_cvt_pk_bf16_f32 v167, v167, v173
	s_waitcnt lgkmcnt(0)
	v_mfma_f32_32x32x16_bf16 v[82:97], v[186:189], v[98:101], v[82:97]
	v_mov_b32_e32 v228, v227
	s_nop 1
	v_permlane32_swap_b32_e32 v227, v228
	v_permlane32_swap_b32_e32 v162, v164
	v_cvt_pk_bf16_f32 v168, v168, v172
	v_cvt_pk_bf16_f32 v169, v169, v171
	v_mfma_f32_32x32x16_bf16 v[66:81], v[230:233], v[98:101], v[66:81]
	v_cvt_pk_bf16_f32 v172, v158, v159
	v_cvt_pk_bf16_f32 v173, v156, v157
	v_cvt_pk_bf16_f32 v174, v150, v151
	v_cvt_pk_bf16_f32 v175, v148, v149
	v_cvt_pk_bf16_f32 v230, v146, v147
	v_cvt_pk_bf16_f32 v231, v160, v161
	v_cvt_pk_bf16_f32 v232, v154, v155
	v_cvt_pk_bf16_f32 v233, v152, v153
	v_permlane32_swap_b32_e32 v163, v165
	v_permlane32_swap_b32_e32 v166, v168
	v_permlane32_swap_b32_e32 v167, v169
	v_permlane32_swap_b32_e32 v172, v174
	v_permlane32_swap_b32_e32 v173, v175
	v_permlane32_swap_b32_e32 v230, v232
	v_permlane32_swap_b32_e32 v231, v233
	s_waitcnt vmcnt(0)
	ds_write_b128 v216, v[130:133]
	ds_write_b128 v217, v[134:137]
	ds_write_b128 v214, v[138:141] offset:32768
	ds_write_b128 v215, v[142:145] offset:32768
	v_lshl_add_u64 v[196:197], v[192:193], 0, v[0:1]
	s_mov_b32 s1, 0x18fb0000
	v_add_co_u32_e32 v146, vcc, s1, v196
	s_mov_b32 s1, 0x18ff8000
	s_nop 0
	v_addc_co_u32_e32 v147, vcc, 0, v197, vcc
	v_add_co_u32_e32 v150, vcc, s1, v196
	v_lshl_add_u64 v[194:195], v[190:191], 0, v[0:1]
	s_nop 0
	v_addc_co_u32_e32 v151, vcc, 0, v197, vcc
	s_mov_b32 s1, 0x1f648000
	v_add_co_u32_e32 v154, vcc, s1, v194
	s_mov_b32 s1, 0x1f654000
	s_nop 0
	v_addc_co_u32_e32 v155, vcc, 0, v195, vcc
	v_add_co_u32_e32 v158, vcc, s1, v194
	global_load_dwordx4 v[146:149], v[146:147], off
	s_nop 0
	global_load_dwordx4 v[150:153], v[150:151], off
	v_addc_co_u32_e32 v159, vcc, 0, v195, vcc
	global_load_dwordx4 v[154:157], v[154:155], off
	s_nop 0
	global_load_dwordx4 v[158:161], v[158:159], off
	ds_read_b64_tr_b16 v[234:235], v213 offset:0
	ds_read_b64_tr_b16 v[236:237], v213 offset:0x800
	ds_read_b64_tr_b16 v[238:239], v213 offset:0x1000
	ds_read_b64_tr_b16 v[240:241], v213 offset:0x1800
	ds_read_b64_tr_b16 v[242:243], v213 offset:0x2000
	ds_read_b64_tr_b16 v[244:245], v213 offset:0x2800
	ds_read_b64_tr_b16 v[246:247], v213 offset:0x3000
	ds_read_b64_tr_b16 v[248:249], v213 offset:0x3800
	s_waitcnt lgkmcnt(4)
; #define SBAR() __builtin_amdgcn_sched_barrier(0)
; __device__ __forceinline__ void partialSM(f32x16& p0, f32x16& p1, float& m_reg, float& mn, float& alpha) {
;   constexpr float C = SCALE * 1.4426950408889634f;
;   float pmax = p0[0];
; #pragma unroll
;   for (int r = 1; r < 16; ++r) pmax = fmaxf(pmax, p0[r]);
; #pragma unroll
;   for (int r = 0; r < 16; ++r) pmax = fmaxf(pmax, p1[r]);
;   { auto rr = __builtin_amdgcn_permlane32_swap(__float_as_uint(pmax), __float_as_uint(pmax), false, false);
;     pmax = fmaxf(__uint_as_float(rr[0]), __uint_as_float(rr[1])); }
;   if (__builtin_expect(__all(pmax - m_reg <= THR / SCALE), 1)) { mn = m_reg; alpha = 1.f; }
;   else { mn = fmaxf(m_reg, pmax); alpha = __builtin_amdgcn_exp2f((m_reg - mn) * C); m_reg = mn; }
; template <int D0> __device__ __forceinline__ void pv_one(f32x16& od, int vb, bf16x8 pa0, bf16x8 pa1, bf16x8 pa2, bf16x8 pa3) {
;   const s16x4 l0 = tr_read<v_rd_off(D0, 0, 0)>(vb), h0 = tr_read<v_rd_off(D0, 0, 1)>(vb), l1 = tr_read<v_rd_off(D0, 1, 0)>(vb), h1 = tr_read<v_rd_off(D0, 1, 1)>(vb);
;   const s16x4 l2 = tr_read<v_rd_off(D0, 2, 0)>(vb), h2 = tr_read<v_rd_off(D0, 2, 1)>(vb), l3 = tr_read<v_rd_off(D0, 3, 0)>(vb), h3 = tr_read<v_rd_off(D0, 3, 1)>(vb);
;   asm volatile("s_waitcnt lgkmcnt(0)" ::: "memory"); SBAR();
;     ...
;   od = __builtin_amdgcn_mfma_f32_32x32x16_bf16(pa0, PK(l0, h0), od, 0, 0, 0);
;   od = __builtin_amdgcn_mfma_f32_32x32x16_bf16(pa1, PK(l1, h1), od, 0, 0, 0);
;   od = __builtin_amdgcn_mfma_f32_32x32x16_bf16(pa2, PK(l2, h2), od, 0, 0, 0);
;   od = __builtin_amdgcn_mfma_f32_32x32x16_bf16(pa3, PK(l3, h3), od, 0, 0, 0);
;     ...
; }
; __device__ __forceinline__ void pv_d0(f32x16* o, int vb, bf16x8 pa0, bf16x8 pa1, bf16x8 pa2, bf16x8 pa3) {
;   pv_one<0>(o[0], vb, pa0, pa1, pa2, pa3); pv_one<1>(o[1], vb, pa0, pa1, pa2, pa3); pv_one<2>(o[2], vb, pa0, pa1, pa2, pa3); pv_one<3>(o[3], vb, pa0, pa1, pa2, pa3);
; }
; template <int DLO, int DHI>
; __device__ __forceinline__ void attn_dense_body(const int g_wave, const bf16* __restrict__ Qb, const bf16* __restrict__ Kh, const bf16* __restrict__ Vh,
;                                                 bf16* __restrict__ Ob, int ldo, char* lds) {
;   const int wid = launder_s(g_wave), lane = opaque_lane(), tid = (wid << 6) | lane, r32 = lane & 31, hi = lane >> 5;
;   bf16* V_lds = (bf16*)lds; bf16* K_lds = (bf16*)(lds + 2 * SHM_V);
	s_nop 0
	v_mfma_f32_32x32x16_bf16 v[2:17], v[162:165], v[234:237], v[2:17]
	ds_read_b64_tr_b16 v[234:235], v213 offset:0x200
	ds_read_b64_tr_b16 v[236:237], v213 offset:0xa00
	v_mfma_f32_32x32x16_bf16 v[2:17], v[166:169], v[238:241], v[2:17]
	ds_read_b64_tr_b16 v[238:239], v213 offset:0x1200
	ds_read_b64_tr_b16 v[240:241], v213 offset:0x1a00
	s_waitcnt lgkmcnt(4)
	v_mfma_f32_32x32x16_bf16 v[2:17], v[172:175], v[242:245], v[2:17]
	ds_read_b64_tr_b16 v[242:243], v213 offset:0x2200
	ds_read_b64_tr_b16 v[244:245], v213 offset:0x2a00
	v_mfma_f32_32x32x16_bf16 v[2:17], v[230:233], v[246:249], v[2:17]
	ds_read_b64_tr_b16 v[246:247], v213 offset:0x3200
	ds_read_b64_tr_b16 v[248:249], v213 offset:0x3a00
	s_waitcnt lgkmcnt(4)
	v_mfma_f32_32x32x16_bf16 v[50:65], v[162:165], v[234:237], v[50:65]
	ds_read_b64_tr_b16 v[234:235], v213 offset:0x400
	ds_read_b64_tr_b16 v[236:237], v213 offset:0xc00
	v_mfma_f32_32x32x16_bf16 v[50:65], v[166:169], v[238:241], v[50:65]
	ds_read_b64_tr_b16 v[238:239], v213 offset:0x1400
	ds_read_b64_tr_b16 v[240:241], v213 offset:0x1c00
	s_waitcnt lgkmcnt(4)
	v_mfma_f32_32x32x16_bf16 v[50:65], v[172:175], v[242:245], v[50:65]
	ds_read_b64_tr_b16 v[242:243], v213 offset:0x2400
	ds_read_b64_tr_b16 v[244:245], v213 offset:0x2c00
	v_mfma_f32_32x32x16_bf16 v[50:65], v[230:233], v[246:249], v[50:65]
	ds_read_b64_tr_b16 v[246:247], v213 offset:0x3400
	ds_read_b64_tr_b16 v[248:249], v213 offset:0x3c00
	s_waitcnt lgkmcnt(4)
	v_mfma_f32_32x32x16_bf16 v[34:49], v[162:165], v[234:237], v[34:49]
	ds_read_b64_tr_b16 v[234:235], v213 offset:0x600
	ds_read_b64_tr_b16 v[236:237], v213 offset:0xe00
	v_mfma_f32_32x32x16_bf16 v[34:49], v[166:169], v[238:241], v[34:49]
	ds_read_b64_tr_b16 v[238:239], v213 offset:0x1600
	ds_read_b64_tr_b16 v[240:241], v213 offset:0x1e00
	s_waitcnt lgkmcnt(4)
	v_mfma_f32_32x32x16_bf16 v[34:49], v[172:175], v[242:245], v[34:49]
	ds_read_b64_tr_b16 v[242:243], v213 offset:0x2600
	ds_read_b64_tr_b16 v[244:245], v213 offset:0x2e00
	v_mfma_f32_32x32x16_bf16 v[34:49], v[230:233], v[246:249], v[34:49]
	ds_read_b64_tr_b16 v[246:247], v213 offset:0x3600
	ds_read_b64_tr_b16 v[248:249], v213 offset:0x3e00
	s_waitcnt lgkmcnt(4)
	v_mfma_f32_32x32x16_bf16 v[18:33], v[162:165], v[234:237], v[18:33]
	v_max_f32_e32 v162, v83, v83
	v_max_f32_e32 v163, v82, v82
	v_max_f32_e32 v162, v163, v162
	v_max3_f32 v162, v162, v84, v85
	v_max3_f32 v162, v162, v86, v87
	v_max3_f32 v162, v162, v88, v89
	v_max3_f32 v162, v162, v90, v91
	v_max3_f32 v162, v162, v92, v93
	v_max3_f32 v162, v162, v94, v95
	v_mfma_f32_32x32x16_bf16 v[18:33], v[166:169], v[238:241], v[18:33]
	v_max3_f32 v162, v162, v96, v97
	v_max3_f32 v162, v162, v66, v67
	v_max3_f32 v162, v162, v68, v69
	v_max3_f32 v162, v162, v70, v71
	v_max3_f32 v162, v162, v72, v73
	v_max3_f32 v162, v162, v74, v75
	v_max3_f32 v162, v162, v76, v77
	v_max3_f32 v162, v162, v78, v79
	s_waitcnt lgkmcnt(0)
	v_mfma_f32_32x32x16_bf16 v[18:33], v[172:175], v[242:245], v[18:33]
	v_max3_f32 v162, v162, v80, v81
	v_mov_b32_e32 v163, v162
	s_nop 1
	v_permlane32_swap_b32_e32 v162, v163
	v_max_f32_e32 v163, v163, v163
	v_max_f32_e32 v162, v162, v162
	v_max_f32_e32 v162, v162, v163
	v_sub_f32_e32 v163, v162, v170
	v_cmp_ge_f32_e32 vcc, s63, v163
	v_max_f32_e32 v163, v170, v170
	v_max_f32_e32 v162, v163, v162
	v_mfma_f32_32x32x16_bf16 v[18:33], v[230:233], v[246:249], v[18:33]
	v_sub_f32_e32 v163, v170, v162
	v_mul_f32_e32 v163, 0x3e0293ee, v163
	v_exp_f32_e32 v163, v163
	s_cmp_eq_u64 vcc, exec
	s_cselect_b64 s[8:9], -1, 0
	v_cndmask_b32_e64 v229, v163, 1.0, s[8:9]
	v_cmp_gt_f32_e32 vcc, 1.0, v229
	s_cbranch_vccz .LBB0_1047
	s_and_saveexec_b64 s[2:3], s[6:7]
	ds_write_b32 v210, v229 offset:128
	s_or_b64 exec, exec, s[2:3]
	s_waitcnt lgkmcnt(0)
	v_add_u32_e32 v163, s15, v209
	ds_read_b128 v[164:167], v163 offset:224
	ds_read_b128 v[172:175], v163 offset:192
	ds_read_b128 v[230:233], v163 offset:160
	ds_read_b128 v[234:237], v163 offset:128
	s_waitcnt lgkmcnt(3)
	v_pk_mul_f32 v[14:15], v[14:15], v[164:165]
	s_waitcnt lgkmcnt(2)
	v_pk_mul_f32 v[10:11], v[10:11], v[172:173]
	s_waitcnt lgkmcnt(1)
	v_pk_mul_f32 v[6:7], v[6:7], v[230:231]
	v_pk_mul_f32 v[16:17], v[16:17], v[166:167]
	v_pk_mul_f32 v[12:13], v[12:13], v[174:175]
	v_pk_mul_f32 v[8:9], v[8:9], v[232:233]
	s_waitcnt lgkmcnt(0)
	v_pk_mul_f32 v[4:5], v[4:5], v[236:237]
	v_pk_mul_f32 v[2:3], v[2:3], v[234:235]
	v_pk_mul_f32 v[62:63], v[62:63], v[164:165]
	v_pk_mul_f32 v[58:59], v[58:59], v[172:173]
	v_pk_mul_f32 v[54:55], v[54:55], v[230:231]
	v_pk_mul_f32 v[64:65], v[64:65], v[166:167]
	v_pk_mul_f32 v[60:61], v[60:61], v[174:175]
	v_pk_mul_f32 v[56:57], v[56:57], v[232:233]
	v_pk_mul_f32 v[52:53], v[52:53], v[236:237]
	v_pk_mul_f32 v[50:51], v[50:51], v[234:235]
	v_pk_mul_f32 v[46:47], v[46:47], v[164:165]
	v_pk_mul_f32 v[42:43], v[42:43], v[172:173]
	v_pk_mul_f32 v[38:39], v[38:39], v[230:231]
	v_pk_mul_f32 v[48:49], v[48:49], v[166:167]
	v_pk_mul_f32 v[44:45], v[44:45], v[174:175]
	v_pk_mul_f32 v[40:41], v[40:41], v[232:233]
	v_pk_mul_f32 v[36:37], v[36:37], v[236:237]
	v_pk_mul_f32 v[34:35], v[34:35], v[234:235]
	v_pk_mul_f32 v[30:31], v[30:31], v[164:165]
	v_pk_mul_f32 v[26:27], v[26:27], v[172:173]
	v_pk_mul_f32 v[22:23], v[22:23], v[230:231]
	v_pk_mul_f32 v[32:33], v[32:33], v[166:167]
	v_pk_mul_f32 v[28:29], v[28:29], v[174:175]
	v_pk_mul_f32 v[24:25], v[24:25], v[232:233]
	v_pk_mul_f32 v[20:21], v[20:21], v[236:237]
	v_pk_mul_f32 v[18:19], v[18:19], v[234:235]

; #define SBAR() __builtin_amdgcn_sched_barrier(0)
; __device__ __forceinline__ void partialSM(f32x16& p0, f32x16& p1, float& m_reg, float& mn, float& alpha) {
;   constexpr float C = SCALE * 1.4426950408889634f;
;   float pmax = p0[0];
; #pragma unroll
;   for (int r = 1; r < 16; ++r) pmax = fmaxf(pmax, p0[r]);
; #pragma unroll
;   for (int r = 0; r < 16; ++r) pmax = fmaxf(pmax, p1[r]);
;   { auto rr = __builtin_amdgcn_permlane32_swap(__float_as_uint(pmax), __float_as_uint(pmax), false, false);
;     pmax = fmaxf(__uint_as_float(rr[0]), __uint_as_float(rr[1])); }
;   if (__builtin_expect(__all(pmax - m_reg <= THR / SCALE), 1)) { mn = m_reg; alpha = 1.f; }
;   else { mn = fmaxf(m_reg, pmax); alpha = __builtin_amdgcn_exp2f((m_reg - mn) * C); m_reg = mn; }
; template <int D0> __device__ __forceinline__ void pv_one(f32x16& od, int vb, bf16x8 pa0, bf16x8 pa1, bf16x8 pa2, bf16x8 pa3) {
;   const s16x4 l0 = tr_read<v_rd_off(D0, 0, 0)>(vb), h0 = tr_read<v_rd_off(D0, 0, 1)>(vb), l1 = tr_read<v_rd_off(D0, 1, 0)>(vb), h1 = tr_read<v_rd_off(D0, 1, 1)>(vb);
;   const s16x4 l2 = tr_read<v_rd_off(D0, 2, 0)>(vb), h2 = tr_read<v_rd_off(D0, 2, 1)>(vb), l3 = tr_read<v_rd_off(D0, 3, 0)>(vb), h3 = tr_read<v_rd_off(D0, 3, 1)>(vb);
;   asm volatile("s_waitcnt lgkmcnt(0)" ::: "memory"); SBAR();
;     ...
;   od = __builtin_amdgcn_mfma_f32_32x32x16_bf16(pa0, PK(l0, h0), od, 0, 0, 0);
;   od = __builtin_amdgcn_mfma_f32_32x32x16_bf16(pa1, PK(l1, h1), od, 0, 0, 0);
;   od = __builtin_amdgcn_mfma_f32_32x32x16_bf16(pa2, PK(l2, h2), od, 0, 0, 0);
;   od = __builtin_amdgcn_mfma_f32_32x32x16_bf16(pa3, PK(l3, h3), od, 0, 0, 0);
;     ...
; }
; __device__ __forceinline__ void pv_d0(f32x16* o, int vb, bf16x8 pa0, bf16x8 pa1, bf16x8 pa2, bf16x8 pa3) {
;   pv_one<0>(o[0], vb, pa0, pa1, pa2, pa3); pv_one<1>(o[1], vb, pa0, pa1, pa2, pa3); pv_one<2>(o[2], vb, pa0, pa1, pa2, pa3); pv_one<3>(o[3], vb, pa0, pa1, pa2, pa3);
; }
; template <int DLO, int DHI>
; __device__ __forceinline__ void attn_dense_body(const int g_wave, const bf16* __restrict__ Qb, const bf16* __restrict__ Kh, const bf16* __restrict__ Vh,
;                                                 bf16* __restrict__ Ob, int ldo, char* lds) {
;   const int wid = launder_s(g_wave), lane = opaque_lane(), tid = (wid << 6) | lane, r32 = lane & 31, hi = lane >> 5;
;   bf16* V_lds = (bf16*)lds; bf16* K_lds = (bf16*)(lds + 2 * SHM_V);
.LBB0_1049:
	ds_read_b64_tr_b16 v[186:187], v212 offset:0
	ds_read_b64_tr_b16 v[188:189], v212 offset:0x800
	ds_read_b64_tr_b16 v[194:195], v212 offset:0x1000
	ds_read_b64_tr_b16 v[196:197], v212 offset:0x1800
	ds_read_b64_tr_b16 v[234:235], v212 offset:0x2000
	ds_read_b64_tr_b16 v[236:237], v212 offset:0x2800
	ds_read_b64_tr_b16 v[238:239], v212 offset:0x3000
	ds_read_b64_tr_b16 v[240:241], v212 offset:0x3800
	s_waitcnt lgkmcnt(4)
	s_nop 0
	v_mfma_f32_32x32x16_bf16 v[2:17], v[162:165], v[186:189], v[2:17]
	ds_read_b64_tr_b16 v[186:187], v212 offset:0x200
	ds_read_b64_tr_b16 v[188:189], v212 offset:0xa00
	v_mfma_f32_32x32x16_bf16 v[2:17], v[166:169], v[194:197], v[2:17]
	ds_read_b64_tr_b16 v[194:195], v212 offset:0x1200
	ds_read_b64_tr_b16 v[196:197], v212 offset:0x1a00
	s_waitcnt lgkmcnt(4)
	v_mfma_f32_32x32x16_bf16 v[2:17], v[170:173], v[234:237], v[2:17]
	ds_read_b64_tr_b16 v[234:235], v212 offset:0x2200
	ds_read_b64_tr_b16 v[236:237], v212 offset:0x2a00
	v_mfma_f32_32x32x16_bf16 v[2:17], v[174:177], v[238:241], v[2:17]
	ds_read_b64_tr_b16 v[238:239], v212 offset:0x3200
	ds_read_b64_tr_b16 v[240:241], v212 offset:0x3a00
	s_waitcnt lgkmcnt(4)
	v_mfma_f32_32x32x16_bf16 v[50:65], v[162:165], v[186:189], v[50:65]
	ds_read_b64_tr_b16 v[186:187], v212 offset:0x400
	ds_read_b64_tr_b16 v[188:189], v212 offset:0xc00
	v_mfma_f32_32x32x16_bf16 v[50:65], v[166:169], v[194:197], v[50:65]
	ds_read_b64_tr_b16 v[194:195], v212 offset:0x1400
	ds_read_b64_tr_b16 v[196:197], v212 offset:0x1c00
	s_waitcnt lgkmcnt(4)
	v_mfma_f32_32x32x16_bf16 v[50:65], v[170:173], v[234:237], v[50:65]
	ds_read_b64_tr_b16 v[234:235], v212 offset:0x2400
	ds_read_b64_tr_b16 v[236:237], v212 offset:0x2c00
	v_mfma_f32_32x32x16_bf16 v[50:65], v[174:177], v[238:241], v[50:65]
	ds_read_b64_tr_b16 v[238:239], v212 offset:0x3400
	ds_read_b64_tr_b16 v[240:241], v212 offset:0x3c00
	s_waitcnt lgkmcnt(4)
	v_mfma_f32_32x32x16_bf16 v[34:49], v[162:165], v[186:189], v[34:49]
	ds_read_b64_tr_b16 v[186:187], v212 offset:0x600
	ds_read_b64_tr_b16 v[188:189], v212 offset:0xe00
	v_mfma_f32_32x32x16_bf16 v[34:49], v[166:169], v[194:197], v[34:49]
	ds_read_b64_tr_b16 v[194:195], v212 offset:0x1600
	ds_read_b64_tr_b16 v[196:197], v212 offset:0x1e00
	s_waitcnt lgkmcnt(4)
	v_mfma_f32_32x32x16_bf16 v[34:49], v[170:173], v[234:237], v[34:49]
	ds_read_b64_tr_b16 v[234:235], v212 offset:0x2600
	ds_read_b64_tr_b16 v[236:237], v212 offset:0x2e00
	v_mfma_f32_32x32x16_bf16 v[34:49], v[174:177], v[238:241], v[34:49]
	ds_read_b64_tr_b16 v[238:239], v212 offset:0x3600
	ds_read_b64_tr_b16 v[240:241], v212 offset:0x3e00
	s_waitcnt lgkmcnt(4)
	v_mfma_f32_32x32x16_bf16 v[18:33], v[162:165], v[186:189], v[18:33]
	v_max_f32_e32 v162, v83, v83
	v_max_f32_e32 v163, v82, v82
	v_max_f32_e32 v162, v163, v162
	v_max3_f32 v162, v162, v84, v85
	v_max3_f32 v162, v162, v86, v87
	v_max3_f32 v162, v162, v88, v89
	v_max3_f32 v162, v162, v90, v91
	v_max3_f32 v162, v162, v92, v93
	v_max3_f32 v162, v162, v94, v95
	v_mfma_f32_32x32x16_bf16 v[18:33], v[166:169], v[194:197], v[18:33]
	v_max3_f32 v162, v162, v96, v97
	v_max3_f32 v162, v162, v66, v67
	v_max3_f32 v162, v162, v68, v69
	v_max3_f32 v162, v162, v70, v71
	v_max3_f32 v162, v162, v72, v73
	v_max3_f32 v162, v162, v74, v75
	v_max3_f32 v162, v162, v76, v77
	v_max3_f32 v162, v162, v78, v79
	s_waitcnt lgkmcnt(0)
	v_mfma_f32_32x32x16_bf16 v[18:33], v[170:173], v[234:237], v[18:33]
	v_max3_f32 v162, v162, v80, v81
	v_mov_b32_e32 v163, v162
	s_nop 1
	v_permlane32_swap_b32_e32 v162, v163
	v_max_f32_e32 v163, v163, v163
	v_max_f32_e32 v162, v162, v162
	v_max_f32_e32 v162, v162, v163
	v_sub_f32_e32 v163, v162, v230
	v_cmp_ge_f32_e32 vcc, s63, v163
	v_max_f32_e32 v163, v230, v230
	v_max_f32_e32 v163, v163, v162
	v_mfma_f32_32x32x16_bf16 v[18:33], v[174:177], v[238:241], v[18:33]
	v_sub_f32_e32 v162, v230, v163
	v_mul_f32_e32 v162, 0x3e0293ee, v162
	v_exp_f32_e32 v162, v162
	s_cmp_eq_u64 vcc, exec
	s_cselect_b64 s[8:9], -1, 0
	v_cndmask_b32_e64 v162, v162, 1.0, s[8:9]
	v_cmp_gt_f32_e32 vcc, 1.0, v162
	s_cbranch_vccz .LBB0_1053
	s_and_saveexec_b64 s[4:5], s[6:7]
	ds_write_b32 v210, v162 offset:128
	s_or_b64 exec, exec, s[4:5]
	s_waitcnt lgkmcnt(0)
	v_add_u32_e32 v158, s15, v209
	ds_read_b128 v[146:149], v158 offset:224
	ds_read_b128 v[150:153], v158 offset:192
	ds_read_b128 v[154:157], v158 offset:160
	ds_read_b128 v[158:161], v158 offset:128
	s_waitcnt lgkmcnt(3)
	v_pk_mul_f32 v[14:15], v[14:15], v[146:147]
	s_waitcnt lgkmcnt(2)
	v_pk_mul_f32 v[10:11], v[10:11], v[150:151]
	s_waitcnt lgkmcnt(1)
	v_pk_mul_f32 v[6:7], v[6:7], v[154:155]
	v_pk_mul_f32 v[16:17], v[16:17], v[148:149]
	v_pk_mul_f32 v[12:13], v[12:13], v[152:153]
	v_pk_mul_f32 v[8:9], v[8:9], v[156:157]
	s_waitcnt lgkmcnt(0)
	v_pk_mul_f32 v[4:5], v[4:5], v[160:161]
	v_pk_mul_f32 v[2:3], v[2:3], v[158:159]
	v_pk_mul_f32 v[62:63], v[62:63], v[146:147]
	v_pk_mul_f32 v[58:59], v[58:59], v[150:151]
	v_pk_mul_f32 v[54:55], v[54:55], v[154:155]
	v_pk_mul_f32 v[64:65], v[64:65], v[148:149]
	v_pk_mul_f32 v[60:61], v[60:61], v[152:153]
	v_pk_mul_f32 v[56:57], v[56:57], v[156:157]
	v_pk_mul_f32 v[52:53], v[52:53], v[160:161]
	v_pk_mul_f32 v[50:51], v[50:51], v[158:159]
	v_pk_mul_f32 v[46:47], v[46:47], v[146:147]
	v_pk_mul_f32 v[42:43], v[42:43], v[150:151]
	v_pk_mul_f32 v[38:39], v[38:39], v[154:155]
	v_pk_mul_f32 v[48:49], v[48:49], v[148:149]
	v_pk_mul_f32 v[44:45], v[44:45], v[152:153]
	v_pk_mul_f32 v[40:41], v[40:41], v[156:157]
	v_pk_mul_f32 v[36:37], v[36:37], v[160:161]
	v_pk_mul_f32 v[34:35], v[34:35], v[158:159]
	v_pk_mul_f32 v[30:31], v[30:31], v[146:147]
	v_pk_mul_f32 v[26:27], v[26:27], v[150:151]
	v_pk_mul_f32 v[22:23], v[22:23], v[154:155]
	v_pk_mul_f32 v[32:33], v[32:33], v[148:149]
	v_pk_mul_f32 v[28:29], v[28:29], v[152:153]
	v_pk_mul_f32 v[24:25], v[24:25], v[156:157]
	v_pk_mul_f32 v[20:21], v[20:21], v[160:161]
	v_pk_mul_f32 v[18:19], v[18:19], v[158:159]
